# poll throttling: the cooperative-groups grid-sync spin loop sleeps 8 instead of 1 between sc1 polls (256 workgroups polling one word)
# speedup vs baseline: 1.0039x; 1.0025x over previous
; __global__ void __launch_bounds__(NTHREADS, 2) fwd_megakernel(Params p) {
;     ...
;     grid.sync();
.LBB0_76:
	s_sleep 8
	global_load_dword v2, v0, s[6:7] offset:32 sc1
	s_waitcnt vmcnt(0)
	v_and_b32_e32 v2, 0xffff0000, v2
	v_cmp_ne_u32_e32 vcc, v2, v1
	s_or_b64 s[8:9], vcc, s[8:9]
	s_andn2_b64 exec, exec, s[8:9]
	s_cbranch_execnz .LBB0_76
